# flatten XCD barrier release: last leader bumps all XGEN words directly
# speedup vs baseline: 1.0212x; 1.0212x over previous
.LBB0_158:
	s_or_b64 exec, exec, s[8:9]
	s_and_saveexec_b64 s[8:9], s[12:13]
	s_cbranch_execz .LBB0_160
	v_mov_b32_e32 v2, 1
	global_atomic_add v[0:1], v2, off
	v_readlane_b32 s98, v255, 1
	v_readlane_b32 s99, v255, 2
	v_mov_b32_e32 v3, 0x2400
	s_nop 3
	global_atomic_add v3, v2, s[98:99]
	global_atomic_add v3, v2, s[98:99] offset:256
	global_atomic_add v3, v2, s[98:99] offset:512
	global_atomic_add v3, v2, s[98:99] offset:768
	global_atomic_add v3, v2, s[98:99] offset:1024
	global_atomic_add v3, v2, s[98:99] offset:1280
	global_atomic_add v3, v2, s[98:99] offset:1536
	global_atomic_add v3, v2, s[98:99] offset:1792
	global_atomic_add v3, v2, s[98:99] offset:2048
	global_atomic_add v3, v2, s[98:99] offset:2304
	global_atomic_add v3, v2, s[98:99] offset:2560
	global_atomic_add v3, v2, s[98:99] offset:2816
	global_atomic_add v3, v2, s[98:99] offset:3072
	global_atomic_add v3, v2, s[98:99] offset:3328
	global_atomic_add v3, v2, s[98:99] offset:3584
	global_atomic_add v3, v2, s[98:99] offset:3840
.LBB0_160:
	s_or_b64 exec, exec, s[8:9]
	s_mov_b64 s[8:9], exec
	v_mbcnt_lo_u32_b32 v0, s8, 0
	v_mbcnt_hi_u32_b32 v0, s9, v0
	v_cmp_eq_u32_e32 vcc, 0, v0
	s_waitcnt vmcnt(0)
	buffer_inv sc1
	s_and_saveexec_b64 s[10:11], vcc
	s_cbranch_execz .LBB0_162
	s_bcnt1_i32_b64 s0, s[8:9]
	v_mov_b32_e32 v0, 0x2000
	v_mov_b32_e32 v1, s0
.LBB0_162:
	s_or_b64 exec, exec, s[10:11]
	s_waitcnt vmcnt(0)

.LBB0_279:
	s_or_b64 exec, exec, s[8:9]
	s_and_saveexec_b64 s[8:9], s[16:17]
	s_cbranch_execz .LBB0_281
	v_mov_b32_e32 v2, 1
	global_atomic_add v[0:1], v2, off
	v_readlane_b32 s98, v255, 1
	v_readlane_b32 s99, v255, 2
	v_mov_b32_e32 v3, 0x2400
	s_nop 3
	global_atomic_add v3, v2, s[98:99]
	global_atomic_add v3, v2, s[98:99] offset:256
	global_atomic_add v3, v2, s[98:99] offset:512
	global_atomic_add v3, v2, s[98:99] offset:768
	global_atomic_add v3, v2, s[98:99] offset:1024
	global_atomic_add v3, v2, s[98:99] offset:1280
	global_atomic_add v3, v2, s[98:99] offset:1536
	global_atomic_add v3, v2, s[98:99] offset:1792
	global_atomic_add v3, v2, s[98:99] offset:2048
	global_atomic_add v3, v2, s[98:99] offset:2304
	global_atomic_add v3, v2, s[98:99] offset:2560
	global_atomic_add v3, v2, s[98:99] offset:2816
	global_atomic_add v3, v2, s[98:99] offset:3072
	global_atomic_add v3, v2, s[98:99] offset:3328
	global_atomic_add v3, v2, s[98:99] offset:3584
	global_atomic_add v3, v2, s[98:99] offset:3840
.LBB0_281:
	s_or_b64 exec, exec, s[8:9]
	s_mov_b64 s[8:9], exec
	v_mbcnt_lo_u32_b32 v0, s8, 0
	v_mbcnt_hi_u32_b32 v0, s9, v0
	v_cmp_eq_u32_e32 vcc, 0, v0
	s_waitcnt vmcnt(0)
	buffer_inv sc1
	s_and_saveexec_b64 s[14:15], vcc
	s_cbranch_execz .LBB0_283
	s_bcnt1_i32_b64 s0, s[8:9]
	v_mov_b32_e32 v0, 0x2000
	v_mov_b32_e32 v1, s0
.LBB0_283:
	s_or_b64 exec, exec, s[14:15]
	s_waitcnt vmcnt(0)

.LBB0_377:
	s_or_b64 exec, exec, s[8:9]
	s_mov_b64 s[8:9], exec
	v_mbcnt_lo_u32_b32 v0, s8, 0
	v_mbcnt_hi_u32_b32 v0, s9, v0
	v_cmp_eq_u32_e32 vcc, 0, v0
	s_waitcnt vmcnt(0)
	buffer_inv sc1
	s_and_saveexec_b64 s[10:11], vcc
	s_cbranch_execz .LBB0_379
	s_bcnt1_i32_b64 s0, s[8:9]
	v_mov_b32_e32 v0, 0x2000
	v_mov_b32_e32 v1, s0
.LBB0_379:
	s_or_b64 exec, exec, s[10:11]
	s_waitcnt vmcnt(0)

.LBB0_526:
	s_or_b64 exec, exec, s[8:9]
	s_mov_b64 s[8:9], exec
	v_mbcnt_lo_u32_b32 v0, s8, 0
	v_mbcnt_hi_u32_b32 v0, s9, v0
	v_cmp_eq_u32_e32 vcc, 0, v0
	s_waitcnt vmcnt(0)
	buffer_inv sc1
	s_and_saveexec_b64 s[10:11], vcc
	s_cbranch_execz .LBB0_528
	s_bcnt1_i32_b64 s0, s[8:9]
	v_mov_b32_e32 v0, 0x2000
	v_mov_b32_e32 v1, s0
.LBB0_528:
	s_or_b64 exec, exec, s[10:11]
	s_waitcnt vmcnt(0)

.LBB0_597:
	s_or_b64 exec, exec, s[4:5]
	s_and_saveexec_b64 s[4:5], s[8:9]
	s_cbranch_execz .LBB0_599
	v_mov_b32_e32 v2, 1
	global_atomic_add v[0:1], v2, off
	v_readlane_b32 s98, v255, 1
	v_readlane_b32 s99, v255, 2
	v_mov_b32_e32 v3, 0x2400
	s_nop 3
	global_atomic_add v3, v2, s[98:99]
	global_atomic_add v3, v2, s[98:99] offset:256
	global_atomic_add v3, v2, s[98:99] offset:512
	global_atomic_add v3, v2, s[98:99] offset:768
	global_atomic_add v3, v2, s[98:99] offset:1024
	global_atomic_add v3, v2, s[98:99] offset:1280
	global_atomic_add v3, v2, s[98:99] offset:1536
	global_atomic_add v3, v2, s[98:99] offset:1792
	global_atomic_add v3, v2, s[98:99] offset:2048
	global_atomic_add v3, v2, s[98:99] offset:2304
	global_atomic_add v3, v2, s[98:99] offset:2560
	global_atomic_add v3, v2, s[98:99] offset:2816
	global_atomic_add v3, v2, s[98:99] offset:3072
	global_atomic_add v3, v2, s[98:99] offset:3328
	global_atomic_add v3, v2, s[98:99] offset:3584
	global_atomic_add v3, v2, s[98:99] offset:3840
.LBB0_599:
	s_or_b64 exec, exec, s[4:5]
	s_mov_b64 s[4:5], exec
	v_mbcnt_lo_u32_b32 v0, s4, 0
	v_mbcnt_hi_u32_b32 v0, s5, v0
	v_cmp_eq_u32_e32 vcc, 0, v0
	s_waitcnt vmcnt(0)
	buffer_inv sc1
	s_and_saveexec_b64 s[6:7], vcc
	s_cbranch_execz .LBB0_601
	s_bcnt1_i32_b64 s4, s[4:5]
	v_mov_b32_e32 v0, 0x2000
	v_mov_b32_e32 v1, s4
.LBB0_601:
	s_or_b64 exec, exec, s[6:7]
	s_waitcnt vmcnt(0)
